# GEMM epilogues (SwiGLU + EpiStore): issue the 8 per-row 1/rms loads in one burst and drop the per-block vmcnt(0) that also waited on the previous block's stores
# speedup vs baseline: 1.0052x; 1.0052x over previous
; DI unsigned pk2(float lo, float hi) { f32x2 v = {lo, hi}; bf16x2_t b = __builtin_convertvector(v, bf16x2_t); return __builtin_bit_cast(unsigned, b); }
;     DI void operator()(AccRef acc, const Unit& u, int wr, int wc, int fr, int fq) const {
;         const int row0 = u.pm * 256 + wr * 64 + fr, col0 = u.pn * 256 + wc * 32 + 8 * fq;
;         f32x4 cs[2][2];
; #pragma unroll
;         for (int bj = 0; bj < 2; ++bj) { cs[bj][0] = (f32x4){1.f, 1.f, 1.f, 1.f}; cs[bj][1] = cs[bj][0];
;             if (rs_mode == 2) { cs[bj][0] = *(const f32x4*)(rs + col0 + bj * 128); cs[bj][1] = *(const f32x4*)(rs + col0 + bj * 128 + 4); } }
; #pragma unroll
;         for (int ai = 0; ai < 2; ++ai)
; #pragma unroll
;             for (int m = 0; m < 4; ++m) { const int row = row0 + ai * 128 + m * 16; bf16_t* rowp = O + (size_t)row * ldc + col0;
;                 const float rr = (rs_mode == 1) ? rs[row] : 1.f;
; #pragma unroll
;                 for (int bj = 0; bj < 2; ++bj) { const f32x4 v0 = acc[ai][bj][m][0] * cs[bj][0] * rr, v1 = acc[ai][bj][m][1] * cs[bj][1] * rr;
;                     u32x4 w; w.x = pk2(v0[0], v0[1]); w.y = pk2(v0[2], v0[3]); w.z = pk2(v1[0], v1[1]); w.w = pk2(v1[2], v1[3]);
;                     *(u32x4*)(rowp + bj * 128) = w; } }
.LBB0_672:
	v_readlane_b32 s4, v253, 21
	v_lshl_add_u32 v182, s43, 8, v169
	v_readlane_b32 s5, v253, 22
	v_ashrrev_i32_e32 v183, 31, v182
	v_mov_b32_e32 v186, 1.0
	v_cndmask_b32_e64 v184, 0, 1, s[4:5]
	v_cmp_ne_u32_e64 s[8:9], 1, v184
	s_andn2_b64 vcc, exec, s[4:5]
	v_lshl_add_u64 v[184:185], v[182:183], 2, s[2:3]
	v_mov_b32_e32 v188, 1.0
	s_cbranch_vccnz .LBB0_674
	global_load_dword v188, v[184:185], off
	global_load_dword v196, v[184:185], off offset:64
	global_load_dword v197, v[184:185], off offset:128
	global_load_dword v198, v[184:185], off offset:192
	global_load_dword v199, v[184:185], off offset:512
	global_load_dword v200, v[184:185], off offset:576
	global_load_dword v201, v[184:185], off offset:640
	global_load_dword v202, v[184:185], off offset:704
.LBB0_674:
	v_mad_u64_u32 v[192:193], s[4:5], v182, s60, 0
	v_mov_b32_e32 v194, v193
	v_mad_u64_u32 v[194:195], s[4:5], v183, s60, v[194:195]
	v_mov_b32_e32 v193, v194
	s_waitcnt vmcnt(0)
	v_pk_mul_f32 v[136:137], v[136:137], v[148:149]
	v_pk_mul_f32 v[134:135], v[134:135], v[146:147]
	v_pk_mul_f32 v[132:133], v[132:133], v[152:153]
	v_pk_mul_f32 v[130:131], v[130:131], v[150:151]
	v_lshl_add_u64 v[192:193], v[192:193], 1, s[50:51]
	v_pk_mul_f32 v[136:137], v[136:137], v[188:189] op_sel_hi:[1,0]
	v_pk_mul_f32 v[134:135], v[134:135], v[188:189] op_sel_hi:[1,0]
	v_pk_mul_f32 v[194:195], v[132:133], v[188:189] op_sel_hi:[1,0]
	v_pk_mul_f32 v[132:133], v[130:131], v[188:189] op_sel_hi:[1,0]
	v_lshl_add_u64 v[192:193], v[180:181], 1, v[192:193]
	v_cvt_pk_bf16_f32 v130, v134, v135
	v_cvt_pk_bf16_f32 v131, v136, v137
	v_cvt_pk_bf16_f32 v132, v132, v133
	v_cvt_pk_bf16_f32 v133, v194, v195
	global_store_dwordx4 v[192:193], v[130:133], off
	v_pk_mul_f32 v[136:137], v[138:139], v[158:159]
	s_and_b64 vcc, exec, s[8:9]
	v_pk_mul_f32 v[130:131], v[144:145], v[156:157]
	v_pk_mul_f32 v[132:133], v[142:143], v[154:155]
	v_pk_mul_f32 v[134:135], v[130:131], v[188:189] op_sel_hi:[1,0]
	v_pk_mul_f32 v[130:131], v[132:133], v[188:189] op_sel_hi:[1,0]
	v_pk_mul_f32 v[132:133], v[140:141], v[160:161]
	v_cvt_pk_bf16_f32 v130, v130, v131
	v_pk_mul_f32 v[138:139], v[132:133], v[188:189] op_sel_hi:[1,0]
	v_pk_mul_f32 v[132:133], v[136:137], v[188:189] op_sel_hi:[1,0]
	v_cvt_pk_bf16_f32 v131, v134, v135
	v_cvt_pk_bf16_f32 v132, v132, v133
	v_cvt_pk_bf16_f32 v133, v138, v139
	global_store_dwordx4 v[192:193], v[130:133], off offset:256
	s_cbranch_vccnz .LBB0_676
	v_mov_b32_e32 v186, v196
.LBB0_676:
	s_nop 0
	v_or_b32_e32 v130, 16, v182
	v_mad_u64_u32 v[130:131], s[4:5], v130, s60, 0
	v_mov_b32_e32 v132, v131
	v_mad_u64_u32 v[132:133], s[4:5], v183, s60, v[132:133]
	v_mov_b32_e32 v131, v132
	v_pk_mul_f32 v[120:121], v[120:121], v[148:149]
	v_pk_mul_f32 v[118:119], v[118:119], v[146:147]
	v_pk_mul_f32 v[116:117], v[116:117], v[152:153]
	v_pk_mul_f32 v[114:115], v[114:115], v[150:151]
	v_lshl_add_u64 v[130:131], v[130:131], 1, s[50:51]
	v_pk_mul_f32 v[120:121], v[120:121], v[186:187] op_sel_hi:[1,0]
	v_pk_mul_f32 v[118:119], v[118:119], v[186:187] op_sel_hi:[1,0]
	v_pk_mul_f32 v[132:133], v[116:117], v[186:187] op_sel_hi:[1,0]
	v_pk_mul_f32 v[116:117], v[114:115], v[186:187] op_sel_hi:[1,0]
	v_lshl_add_u64 v[130:131], v[180:181], 1, v[130:131]
	v_cvt_pk_bf16_f32 v114, v118, v119
	v_cvt_pk_bf16_f32 v115, v120, v121
	v_cvt_pk_bf16_f32 v116, v116, v117
	v_cvt_pk_bf16_f32 v117, v132, v133
	global_store_dwordx4 v[130:131], v[114:117], off
	v_pk_mul_f32 v[120:121], v[122:123], v[158:159]
	s_and_b64 vcc, exec, s[8:9]
	v_pk_mul_f32 v[114:115], v[128:129], v[156:157]
	v_pk_mul_f32 v[116:117], v[126:127], v[154:155]
	v_pk_mul_f32 v[118:119], v[114:115], v[186:187] op_sel_hi:[1,0]
	v_pk_mul_f32 v[114:115], v[116:117], v[186:187] op_sel_hi:[1,0]
	v_pk_mul_f32 v[116:117], v[124:125], v[160:161]
	v_cvt_pk_bf16_f32 v114, v114, v115
	v_pk_mul_f32 v[122:123], v[116:117], v[186:187] op_sel_hi:[1,0]
	v_pk_mul_f32 v[116:117], v[120:121], v[186:187] op_sel_hi:[1,0]
	v_cvt_pk_bf16_f32 v115, v118, v119
	v_cvt_pk_bf16_f32 v116, v116, v117
	v_cvt_pk_bf16_f32 v117, v122, v123
	global_store_dwordx4 v[130:131], v[114:117], off offset:256
	s_nop 1
	v_mov_b32_e32 v114, 1.0
	v_mov_b32_e32 v116, 1.0
	s_cbranch_vccnz .LBB0_678
	v_mov_b32_e32 v116, v197
.LBB0_678:
	v_or_b32_e32 v115, 32, v182
	v_mad_u64_u32 v[118:119], s[4:5], v115, s60, 0
	v_mov_b32_e32 v120, v119
	v_mad_u64_u32 v[120:121], s[4:5], v183, s60, v[120:121]
	v_mov_b32_e32 v119, v120
	v_pk_mul_f32 v[104:105], v[104:105], v[148:149]
	v_pk_mul_f32 v[102:103], v[102:103], v[146:147]
	v_pk_mul_f32 v[100:101], v[100:101], v[152:153]
	v_pk_mul_f32 v[98:99], v[98:99], v[150:151]
	v_lshl_add_u64 v[118:119], v[118:119], 1, s[50:51]
	v_pk_mul_f32 v[104:105], v[104:105], v[116:117] op_sel_hi:[1,0]
	v_pk_mul_f32 v[102:103], v[102:103], v[116:117] op_sel_hi:[1,0]
	v_pk_mul_f32 v[120:121], v[100:101], v[116:117] op_sel_hi:[1,0]
	v_pk_mul_f32 v[100:101], v[98:99], v[116:117] op_sel_hi:[1,0]
	v_lshl_add_u64 v[118:119], v[180:181], 1, v[118:119]
	v_cvt_pk_bf16_f32 v98, v102, v103
	v_cvt_pk_bf16_f32 v99, v104, v105
	v_cvt_pk_bf16_f32 v100, v100, v101
	v_cvt_pk_bf16_f32 v101, v120, v121
	global_store_dwordx4 v[118:119], v[98:101], off
	v_pk_mul_f32 v[104:105], v[106:107], v[158:159]
	s_and_b64 vcc, exec, s[8:9]
	v_pk_mul_f32 v[98:99], v[112:113], v[156:157]
	v_pk_mul_f32 v[100:101], v[110:111], v[154:155]
	v_pk_mul_f32 v[102:103], v[98:99], v[116:117] op_sel_hi:[1,0]
	v_pk_mul_f32 v[98:99], v[100:101], v[116:117] op_sel_hi:[1,0]
	v_pk_mul_f32 v[100:101], v[108:109], v[160:161]
	v_cvt_pk_bf16_f32 v98, v98, v99
	v_pk_mul_f32 v[106:107], v[100:101], v[116:117] op_sel_hi:[1,0]
	v_pk_mul_f32 v[100:101], v[104:105], v[116:117] op_sel_hi:[1,0]
	v_cvt_pk_bf16_f32 v99, v102, v103
	v_cvt_pk_bf16_f32 v100, v100, v101
	v_cvt_pk_bf16_f32 v101, v106, v107
	global_store_dwordx4 v[118:119], v[98:101], off offset:256
	s_cbranch_vccnz .LBB0_680
	v_mov_b32_e32 v114, v198
; DI unsigned pk2(float lo, float hi) { f32x2 v = {lo, hi}; bf16x2_t b = __builtin_convertvector(v, bf16x2_t); return __builtin_bit_cast(unsigned, b); }
;     DI void operator()(AccRef acc, const Unit& u, int wr, int wc, int fr, int fq) const {
;     ...
;             for (int m = 0; m < 4; ++m) { const int row = row0 + ai * 128 + m * 16; bf16_t* rowp = O + (size_t)row * ldc + col0;
;                 const float rr = (rs_mode == 1) ? rs[row] : 1.f;
; #pragma unroll
;                 for (int bj = 0; bj < 2; ++bj) { const f32x4 v0 = acc[ai][bj][m][0] * cs[bj][0] * rr, v1 = acc[ai][bj][m][1] * cs[bj][1] * rr;
;                     u32x4 w; w.x = pk2(v0[0], v0[1]); w.y = pk2(v0[2], v0[3]); w.z = pk2(v1[0], v1[1]); w.w = pk2(v1[2], v1[3]);
;                     *(u32x4*)(rowp + bj * 128) = w; } }
.LBB0_680:
	s_nop 0
	v_or_b32_e32 v98, 48, v182
	v_mad_u64_u32 v[98:99], s[4:5], v98, s60, 0
	v_mov_b32_e32 v100, v99
	v_mad_u64_u32 v[100:101], s[4:5], v183, s60, v[100:101]
	v_mov_b32_e32 v99, v100
	v_pk_mul_f32 v[70:71], v[70:71], v[148:149]
	v_pk_mul_f32 v[68:69], v[68:69], v[146:147]
	v_pk_mul_f32 v[66:67], v[66:67], v[152:153]
	v_pk_mul_f32 v[64:65], v[64:65], v[150:151]
	v_lshl_add_u64 v[98:99], v[98:99], 1, s[50:51]
	v_pk_mul_f32 v[70:71], v[70:71], v[114:115] op_sel_hi:[1,0]
	v_pk_mul_f32 v[68:69], v[68:69], v[114:115] op_sel_hi:[1,0]
	v_pk_mul_f32 v[100:101], v[66:67], v[114:115] op_sel_hi:[1,0]
	v_pk_mul_f32 v[66:67], v[64:65], v[114:115] op_sel_hi:[1,0]
	v_lshl_add_u64 v[98:99], v[180:181], 1, v[98:99]
	v_cvt_pk_bf16_f32 v64, v68, v69
	v_cvt_pk_bf16_f32 v65, v70, v71
	v_cvt_pk_bf16_f32 v66, v66, v67
	v_cvt_pk_bf16_f32 v67, v100, v101
	global_store_dwordx4 v[98:99], v[64:67], off
	v_pk_mul_f32 v[70:71], v[72:73], v[158:159]
	s_and_b64 vcc, exec, s[8:9]
	v_pk_mul_f32 v[64:65], v[78:79], v[156:157]
	v_pk_mul_f32 v[66:67], v[76:77], v[154:155]
	v_pk_mul_f32 v[68:69], v[64:65], v[114:115] op_sel_hi:[1,0]
	v_pk_mul_f32 v[64:65], v[66:67], v[114:115] op_sel_hi:[1,0]
	v_pk_mul_f32 v[66:67], v[74:75], v[160:161]
	v_cvt_pk_bf16_f32 v64, v64, v65
	v_pk_mul_f32 v[72:73], v[66:67], v[114:115] op_sel_hi:[1,0]
	v_pk_mul_f32 v[66:67], v[70:71], v[114:115] op_sel_hi:[1,0]
	v_cvt_pk_bf16_f32 v65, v68, v69
	v_cvt_pk_bf16_f32 v66, v66, v67
	v_cvt_pk_bf16_f32 v67, v72, v73
	global_store_dwordx4 v[98:99], v[64:67], off offset:256
	s_nop 1
	v_mov_b32_e32 v64, 1.0
	v_mov_b32_e32 v66, 1.0
	s_cbranch_vccnz .LBB0_682
	v_mov_b32_e32 v66, v199
.LBB0_682:
	v_add_u32_e32 v65, 0x80, v182
	v_mad_u64_u32 v[68:69], s[4:5], v65, s60, 0
	v_ashrrev_i32_e32 v67, 31, v65
	v_mov_b32_e32 v70, v69
	v_mad_u64_u32 v[70:71], s[4:5], v67, s60, v[70:71]
	v_mov_b32_e32 v69, v70
	v_pk_mul_f32 v[54:55], v[54:55], v[148:149]
	v_pk_mul_f32 v[52:53], v[52:53], v[146:147]
	v_pk_mul_f32 v[50:51], v[50:51], v[152:153]
	v_pk_mul_f32 v[48:49], v[48:49], v[150:151]
	v_lshl_add_u64 v[68:69], v[68:69], 1, s[50:51]
	v_pk_mul_f32 v[54:55], v[54:55], v[66:67] op_sel_hi:[1,0]
	v_pk_mul_f32 v[52:53], v[52:53], v[66:67] op_sel_hi:[1,0]
	v_pk_mul_f32 v[70:71], v[50:51], v[66:67] op_sel_hi:[1,0]
	v_pk_mul_f32 v[50:51], v[48:49], v[66:67] op_sel_hi:[1,0]
	v_lshl_add_u64 v[68:69], v[180:181], 1, v[68:69]
	v_cvt_pk_bf16_f32 v48, v52, v53
	v_cvt_pk_bf16_f32 v49, v54, v55
	v_cvt_pk_bf16_f32 v50, v50, v51
	v_cvt_pk_bf16_f32 v51, v70, v71
	global_store_dwordx4 v[68:69], v[48:51], off
	v_pk_mul_f32 v[54:55], v[56:57], v[158:159]
	s_and_b64 vcc, exec, s[8:9]
	v_pk_mul_f32 v[48:49], v[62:63], v[156:157]
	v_pk_mul_f32 v[50:51], v[60:61], v[154:155]
	v_pk_mul_f32 v[52:53], v[48:49], v[66:67] op_sel_hi:[1,0]
	v_pk_mul_f32 v[48:49], v[50:51], v[66:67] op_sel_hi:[1,0]
	v_pk_mul_f32 v[50:51], v[58:59], v[160:161]
	v_cvt_pk_bf16_f32 v48, v48, v49
	v_pk_mul_f32 v[56:57], v[50:51], v[66:67] op_sel_hi:[1,0]
	v_pk_mul_f32 v[50:51], v[54:55], v[66:67] op_sel_hi:[1,0]
	v_cvt_pk_bf16_f32 v49, v52, v53
	v_cvt_pk_bf16_f32 v50, v50, v51
	v_cvt_pk_bf16_f32 v51, v56, v57
	global_store_dwordx4 v[68:69], v[48:51], off offset:256
	s_cbranch_vccnz .LBB0_684
	v_mov_b32_e32 v64, v200
.LBB0_684:
	s_nop 0
	v_add_u32_e32 v48, 0x90, v182
	v_ashrrev_i32_e32 v51, 31, v48
	v_mad_u64_u32 v[48:49], s[4:5], v48, s60, 0
	v_mov_b32_e32 v50, v49
	v_mad_u64_u32 v[50:51], s[4:5], v51, s60, v[50:51]
	v_mov_b32_e32 v49, v50
	v_pk_mul_f32 v[38:39], v[38:39], v[148:149]
	v_pk_mul_f32 v[36:37], v[36:37], v[146:147]
	v_pk_mul_f32 v[34:35], v[34:35], v[152:153]
	v_pk_mul_f32 v[32:33], v[32:33], v[150:151]
	v_lshl_add_u64 v[48:49], v[48:49], 1, s[50:51]
	v_pk_mul_f32 v[38:39], v[38:39], v[64:65] op_sel_hi:[1,0]
	v_pk_mul_f32 v[36:37], v[36:37], v[64:65] op_sel_hi:[1,0]
	v_pk_mul_f32 v[50:51], v[34:35], v[64:65] op_sel_hi:[1,0]
	v_pk_mul_f32 v[34:35], v[32:33], v[64:65] op_sel_hi:[1,0]
	v_lshl_add_u64 v[48:49], v[180:181], 1, v[48:49]
	v_cvt_pk_bf16_f32 v32, v36, v37
	v_cvt_pk_bf16_f32 v33, v38, v39
	v_cvt_pk_bf16_f32 v34, v34, v35
	v_cvt_pk_bf16_f32 v35, v50, v51
	global_store_dwordx4 v[48:49], v[32:35], off
	v_pk_mul_f32 v[38:39], v[40:41], v[158:159]
	s_and_b64 vcc, exec, s[8:9]
	v_pk_mul_f32 v[32:33], v[46:47], v[156:157]
	v_pk_mul_f32 v[34:35], v[44:45], v[154:155]
	v_pk_mul_f32 v[36:37], v[32:33], v[64:65] op_sel_hi:[1,0]
	v_pk_mul_f32 v[32:33], v[34:35], v[64:65] op_sel_hi:[1,0]
	v_pk_mul_f32 v[34:35], v[42:43], v[160:161]
	v_cvt_pk_bf16_f32 v32, v32, v33
	v_pk_mul_f32 v[40:41], v[34:35], v[64:65] op_sel_hi:[1,0]
	v_pk_mul_f32 v[34:35], v[38:39], v[64:65] op_sel_hi:[1,0]
	v_cvt_pk_bf16_f32 v33, v36, v37
	v_cvt_pk_bf16_f32 v34, v34, v35
	v_cvt_pk_bf16_f32 v35, v40, v41
	global_store_dwordx4 v[48:49], v[32:35], off offset:256
	s_nop 1
	v_mov_b32_e32 v32, 1.0
	v_mov_b32_e32 v34, 1.0
	s_cbranch_vccnz .LBB0_686
	v_mov_b32_e32 v34, v201
; DI unsigned pk2(float lo, float hi) { f32x2 v = {lo, hi}; bf16x2_t b = __builtin_convertvector(v, bf16x2_t); return __builtin_bit_cast(unsigned, b); }
; #define PG8_BAR __builtin_amdgcn_s_barrier()
; template <class Epi>
; DI void gemm_phase(LAS unsigned char* lds, const Gemm g, const StaticOrder& S, const Epi& E) {
;     ...
;         if (!has_next) break;
; #pragma unroll
;         for (int a = 0; a < 2; ++a)
; #pragma unroll
;             for (int b = 0; b < 2; ++b)
; #pragma unroll
;                 for (int m = 0; m < 4; ++m)
; #pragma unroll
;                     for (int n = 0; n < 2; ++n) { float zz = 0.f; asm volatile("" : "+v"(zz)); acc[a][b][m][n] = (f32x4){zz, zz, zz, zz}; }
;         cur = nxt; cA = nA; cB = nB; ++ui;
;         if (wr == 1) PG8_BAR;
;     DI void operator()(AccRef acc, const Unit& u, int wr, int wc, int fr, int fq) const {
;     ...
;             for (int m = 0; m < 4; ++m) { const int row = row0 + ai * 128 + m * 16; bf16_t* rowp = O + (size_t)row * ldc + col0;
;                 const float rr = (rs_mode == 1) ? rs[row] : 1.f;
; #pragma unroll
;                 for (int bj = 0; bj < 2; ++bj) { const f32x4 v0 = acc[ai][bj][m][0] * cs[bj][0] * rr, v1 = acc[ai][bj][m][1] * cs[bj][1] * rr;
;                     u32x4 w; w.x = pk2(v0[0], v0[1]); w.y = pk2(v0[2], v0[3]); w.z = pk2(v1[0], v1[1]); w.w = pk2(v1[2], v1[3]);
;                     *(u32x4*)(rowp + bj * 128) = w; } }
.LBB0_686:
	v_add_u32_e32 v33, 0xa0, v182
	v_mad_u64_u32 v[36:37], s[4:5], v33, s60, 0
	v_ashrrev_i32_e32 v35, 31, v33
	v_mov_b32_e32 v38, v37
	v_mad_u64_u32 v[38:39], s[4:5], v35, s60, v[38:39]
	v_mov_b32_e32 v37, v38
	v_pk_mul_f32 v[22:23], v[22:23], v[148:149]
	v_pk_mul_f32 v[20:21], v[20:21], v[146:147]
	v_pk_mul_f32 v[18:19], v[18:19], v[152:153]
	v_pk_mul_f32 v[16:17], v[16:17], v[150:151]
	v_lshl_add_u64 v[36:37], v[36:37], 1, s[50:51]
	v_pk_mul_f32 v[22:23], v[22:23], v[34:35] op_sel_hi:[1,0]
	v_pk_mul_f32 v[20:21], v[20:21], v[34:35] op_sel_hi:[1,0]
	v_pk_mul_f32 v[38:39], v[18:19], v[34:35] op_sel_hi:[1,0]
	v_pk_mul_f32 v[18:19], v[16:17], v[34:35] op_sel_hi:[1,0]
	v_lshl_add_u64 v[36:37], v[180:181], 1, v[36:37]
	v_cvt_pk_bf16_f32 v16, v20, v21
	v_cvt_pk_bf16_f32 v17, v22, v23
	v_cvt_pk_bf16_f32 v18, v18, v19
	v_cvt_pk_bf16_f32 v19, v38, v39
	global_store_dwordx4 v[36:37], v[16:19], off
	v_pk_mul_f32 v[22:23], v[24:25], v[158:159]
	s_and_b64 vcc, exec, s[8:9]
	v_pk_mul_f32 v[16:17], v[30:31], v[156:157]
	v_pk_mul_f32 v[18:19], v[28:29], v[154:155]
	v_pk_mul_f32 v[20:21], v[16:17], v[34:35] op_sel_hi:[1,0]
	v_pk_mul_f32 v[16:17], v[18:19], v[34:35] op_sel_hi:[1,0]
	v_pk_mul_f32 v[18:19], v[26:27], v[160:161]
	v_cvt_pk_bf16_f32 v16, v16, v17
	v_pk_mul_f32 v[24:25], v[18:19], v[34:35] op_sel_hi:[1,0]
	v_pk_mul_f32 v[18:19], v[22:23], v[34:35] op_sel_hi:[1,0]
	v_cvt_pk_bf16_f32 v17, v20, v21
	v_cvt_pk_bf16_f32 v18, v18, v19
	v_cvt_pk_bf16_f32 v19, v24, v25
	global_store_dwordx4 v[36:37], v[16:19], off offset:256
	s_cbranch_vccnz .LBB0_688
	v_mov_b32_e32 v32, v202
.LBB0_688:
	s_nop 0
	v_add_u32_e32 v16, 0xb0, v182
	v_ashrrev_i32_e32 v19, 31, v16
	v_mad_u64_u32 v[16:17], s[4:5], v16, s60, 0
	v_mov_b32_e32 v18, v17
	v_mad_u64_u32 v[18:19], s[4:5], v19, s60, v[18:19]
	v_mov_b32_e32 v17, v18
	v_pk_mul_f32 v[6:7], v[6:7], v[148:149]
	v_pk_mul_f32 v[4:5], v[4:5], v[146:147]
	v_pk_mul_f32 v[2:3], v[2:3], v[152:153]
	v_pk_mul_f32 v[0:1], v[0:1], v[150:151]
	v_lshl_add_u64 v[16:17], v[16:17], 1, s[50:51]
	v_pk_mul_f32 v[6:7], v[6:7], v[32:33] op_sel_hi:[1,0]
	v_pk_mul_f32 v[4:5], v[4:5], v[32:33] op_sel_hi:[1,0]
	v_pk_mul_f32 v[18:19], v[2:3], v[32:33] op_sel_hi:[1,0]
	v_pk_mul_f32 v[2:3], v[0:1], v[32:33] op_sel_hi:[1,0]
	v_lshl_add_u64 v[16:17], v[180:181], 1, v[16:17]
	v_cvt_pk_bf16_f32 v0, v4, v5
	v_cvt_pk_bf16_f32 v1, v6, v7
	v_cvt_pk_bf16_f32 v2, v2, v3
	v_cvt_pk_bf16_f32 v3, v18, v19
	global_store_dwordx4 v[16:17], v[0:3], off
	v_pk_mul_f32 v[6:7], v[8:9], v[158:159]
	s_and_b64 vcc, exec, s[6:7]
	v_pk_mul_f32 v[0:1], v[14:15], v[156:157]
	v_pk_mul_f32 v[2:3], v[12:13], v[154:155]
	v_pk_mul_f32 v[4:5], v[0:1], v[32:33] op_sel_hi:[1,0]
	v_pk_mul_f32 v[0:1], v[2:3], v[32:33] op_sel_hi:[1,0]
	v_pk_mul_f32 v[2:3], v[10:11], v[160:161]
	v_cvt_pk_bf16_f32 v0, v0, v1
	v_pk_mul_f32 v[8:9], v[2:3], v[32:33] op_sel_hi:[1,0]
	v_pk_mul_f32 v[2:3], v[6:7], v[32:33] op_sel_hi:[1,0]
	v_cvt_pk_bf16_f32 v1, v4, v5
	v_cvt_pk_bf16_f32 v2, v2, v3
	v_cvt_pk_bf16_f32 v3, v8, v9
	s_mov_b64 s[4:5], -1
	global_store_dwordx4 v[16:17], v[0:3], off offset:256
	s_cbranch_vccnz .LBB0_652
	v_mov_b32_e32 v134, 0
	v_mov_b32_e32 v130, 0
	v_mov_b32_e32 v118, 0
	v_mov_b32_e32 v114, 0
	v_mov_b32_e32 v102, 0
	v_mov_b32_e32 v98, 0
	v_mov_b32_e32 v68, 0
	v_mov_b32_e32 v64, 0
	v_mov_b32_e32 v142, 0
	v_mov_b32_e32 v138, 0
	v_mov_b32_e32 v126, 0
	v_mov_b32_e32 v122, 0
	v_mov_b32_e32 v110, 0
	v_mov_b32_e32 v106, 0
	v_mov_b32_e32 v76, 0
	v_mov_b32_e32 v72, 0
	v_mov_b32_e32 v52, 0
	v_mov_b32_e32 v48, 0
	v_mov_b32_e32 v36, 0
	v_mov_b32_e32 v32, 0
	v_mov_b32_e32 v20, 0
	v_mov_b32_e32 v16, 0
	v_mov_b32_e32 v4, 0
	v_mov_b32_e32 v0, 0
	v_mov_b32_e32 v60, 0
	v_mov_b32_e32 v56, 0
	v_mov_b32_e32 v44, 0
	v_mov_b32_e32 v40, 0
	v_mov_b32_e32 v28, 0
	v_mov_b32_e32 v24, 0
	v_mov_b32_e32 v12, 0
	v_mov_b32_e32 v8, 0
	s_andn2_b64 vcc, exec, s[12:13]
	s_cbranch_vccnz .LBB0_651
	s_barrier
	s_branch .LBB0_651

; DI u32x4 pack8f(const float (&f)[8]) { u32x4 w; w.x = pk2(f[0], f[1]); w.y = pk2(f[2], f[3]); w.z = pk2(f[4], f[5]); w.w = pk2(f[6], f[7]); return w; }
; DI float siluf_(float x) { return x * sigmoidf_(x); }
;     DI void operator()(AccRef acc, const Unit& u, int wr, int wc, int fr, int fq) const {
;         const int row0 = u.pm * 256 + wr * 64 + fr, col0 = u.pn * 128 + wc * 32 + 8 * fq;
; #pragma unroll
;         for (int ai = 0; ai < 2; ++ai)
; #pragma unroll
;             for (int m = 0; m < 4; ++m) { const int row = row0 + ai * 128 + m * 16; bf16_t* rowp = O + (size_t)row * ldc + col0; const float rr = rs[row];
;                 float r[8];
; #pragma unroll
;                 for (int n = 0; n < 2; ++n)
; #pragma unroll
;                     for (int e = 0; e < 4; ++e) r[4 * n + e] = siluf_(acc[ai][0][m][n][e] * rr) * (acc[ai][1][m][n][e] * rr);
;                 *(u32x4*)rowp = pack8f(r); }
.LBB0_704:
	v_lshl_add_u32 v156, s38, 8, v163
	v_ashrrev_i32_e32 v157, 31, v156
	v_lshl_add_u64 v[160:161], v[156:157], 2, s[2:3]
	global_load_dword v178, v[160:161], off
	global_load_dword v196, v[160:161], off offset:64
	global_load_dword v197, v[160:161], off offset:128
	global_load_dword v198, v[160:161], off offset:192
	global_load_dword v199, v[160:161], off offset:512
	global_load_dword v200, v[160:161], off offset:576
	global_load_dword v201, v[160:161], off offset:640
	global_load_dword v202, v[160:161], off offset:704
	v_lshl_or_b32 v174, s36, 7, v164
	v_ashrrev_i32_e32 v175, 31, v174
	v_mov_b64_e32 v[158:159], s[88:89]
	v_mad_i64_i32 v[176:177], s[16:17], v156, s50, v[158:159]
	s_andn2_b64 vcc, exec, s[6:7]
	s_waitcnt vmcnt(0)
	v_pk_mul_f32 v[134:135], v[134:135], v[178:179] op_sel_hi:[1,0]
	s_nop 0
	v_mul_f32_e32 v157, 0xbfb8aa3b, v134
	v_exp_f32_e32 v157, v157
	v_pk_mul_f32 v[142:143], v[142:143], v[178:179] op_sel_hi:[1,0]
	v_pk_mul_f32 v[136:137], v[136:137], v[178:179] op_sel_hi:[1,0]
	v_pk_mul_f32 v[130:131], v[130:131], v[178:179] op_sel_hi:[1,0]
	v_add_f32_e32 v157, 1.0, v157
	v_rcp_f32_e32 v180, v157
	v_mul_f32_e32 v157, 0xbfb8aa3b, v135
	v_exp_f32_e32 v157, v157
	v_pk_mul_f32 v[138:139], v[138:139], v[178:179] op_sel_hi:[1,0]
	v_add_f32_e32 v157, 1.0, v157
	v_rcp_f32_e32 v181, v157
	s_nop 0
	v_pk_mul_f32 v[134:135], v[134:135], v[180:181]
	s_nop 0
	v_pk_mul_f32 v[134:135], v[142:143], v[134:135]
	v_mul_f32_e32 v142, 0xbfb8aa3b, v136
	v_mul_f32_e32 v143, 0xbfb8aa3b, v137
	v_exp_f32_e32 v142, v142
	v_exp_f32_e32 v143, v143
	v_add_f32_e32 v142, 1.0, v142
	v_add_f32_e32 v143, 1.0, v143
	v_rcp_f32_e32 v142, v142
	v_rcp_f32_e32 v143, v143
	s_nop 0
	v_pk_mul_f32 v[136:137], v[136:137], v[142:143]
	v_pk_mul_f32 v[142:143], v[144:145], v[178:179] op_sel_hi:[1,0]
	s_nop 0
	v_pk_mul_f32 v[136:137], v[142:143], v[136:137]
	v_mul_f32_e32 v142, 0xbfb8aa3b, v130
	v_mul_f32_e32 v143, 0xbfb8aa3b, v131
	v_exp_f32_e32 v142, v142
	v_exp_f32_e32 v143, v143
	v_add_f32_e32 v142, 1.0, v142
	v_add_f32_e32 v143, 1.0, v143
	v_rcp_f32_e32 v142, v142
	v_rcp_f32_e32 v143, v143
	s_nop 0
	v_pk_mul_f32 v[130:131], v[130:131], v[142:143]
	s_nop 0
	v_pk_mul_f32 v[138:139], v[138:139], v[130:131]
	v_pk_mul_f32 v[130:131], v[132:133], v[178:179] op_sel_hi:[1,0]
	s_nop 0
	v_mul_f32_e32 v132, 0xbfb8aa3b, v130
	v_mul_f32_e32 v133, 0xbfb8aa3b, v131
	v_exp_f32_e32 v132, v132
	v_exp_f32_e32 v133, v133
	v_add_f32_e32 v132, 1.0, v132
	v_add_f32_e32 v133, 1.0, v133
	v_rcp_f32_e32 v132, v132
	v_rcp_f32_e32 v133, v133
	s_nop 0
	v_pk_mul_f32 v[130:131], v[130:131], v[132:133]
	v_pk_mul_f32 v[132:133], v[140:141], v[178:179] op_sel_hi:[1,0]
	s_nop 0
	v_pk_mul_f32 v[140:141], v[132:133], v[130:131]
	v_lshlrev_b64 v[130:131], 1, v[174:175]
	v_lshl_add_u64 v[142:143], v[176:177], 0, v[130:131]
	v_cvt_pk_bf16_f32 v132, v134, v135
	v_cvt_pk_bf16_f32 v133, v136, v137
	v_cvt_pk_bf16_f32 v134, v138, v139
	v_cvt_pk_bf16_f32 v135, v140, v141
	global_store_dwordx4 v[142:143], v[132:135], off
	s_nop 1
	v_or_b32_e32 v134, 16, v156
	v_ashrrev_i32_e32 v135, 31, v134
	v_mad_i64_i32 v[132:133], s[16:17], v134, s50, v[158:159]
	v_lshl_add_u64 v[134:135], v[134:135], 2, s[2:3]
	v_mov_b32_e32 v134, v196
	v_pk_mul_f32 v[118:119], v[118:119], v[134:135] op_sel_hi:[1,0]
	s_nop 0
	v_mul_f32_e32 v135, 0xbfb8aa3b, v118
	v_exp_f32_e32 v135, v135
	s_nop 0
	v_add_f32_e32 v135, 1.0, v135
	v_rcp_f32_e32 v136, v135
	v_mul_f32_e32 v135, 0xbfb8aa3b, v119
	v_exp_f32_e32 v135, v135
	s_nop 0
	v_add_f32_e32 v135, 1.0, v135
	v_rcp_f32_e32 v137, v135
	v_pk_mul_f32 v[126:127], v[126:127], v[134:135] op_sel_hi:[1,0]
	v_pk_mul_f32 v[120:121], v[120:121], v[134:135] op_sel_hi:[1,0]
	v_pk_mul_f32 v[114:115], v[114:115], v[134:135] op_sel_hi:[1,0]
	v_pk_mul_f32 v[118:119], v[118:119], v[136:137]
	v_pk_mul_f32 v[122:123], v[122:123], v[134:135] op_sel_hi:[1,0]
	v_pk_mul_f32 v[118:119], v[126:127], v[118:119]
	v_mul_f32_e32 v126, 0xbfb8aa3b, v120
	v_mul_f32_e32 v127, 0xbfb8aa3b, v121
	v_exp_f32_e32 v126, v126
	v_exp_f32_e32 v127, v127
	v_add_f32_e32 v126, 1.0, v126
	v_add_f32_e32 v127, 1.0, v127
	v_rcp_f32_e32 v126, v126
	v_rcp_f32_e32 v127, v127
	s_nop 0
	v_pk_mul_f32 v[120:121], v[120:121], v[126:127]
	v_pk_mul_f32 v[126:127], v[128:129], v[134:135] op_sel_hi:[1,0]
	s_nop 0
	v_pk_mul_f32 v[120:121], v[126:127], v[120:121]
	v_mul_f32_e32 v126, 0xbfb8aa3b, v114
	v_mul_f32_e32 v127, 0xbfb8aa3b, v115
	v_exp_f32_e32 v126, v126
	v_exp_f32_e32 v127, v127
	v_add_f32_e32 v126, 1.0, v126
	v_add_f32_e32 v127, 1.0, v127
	v_rcp_f32_e32 v126, v126
	v_rcp_f32_e32 v127, v127
	s_nop 0
	v_pk_mul_f32 v[114:115], v[114:115], v[126:127]
	s_nop 0
	v_pk_mul_f32 v[122:123], v[122:123], v[114:115]
	v_pk_mul_f32 v[114:115], v[116:117], v[134:135] op_sel_hi:[1,0]
	v_lshl_add_u64 v[126:127], v[132:133], 0, v[130:131]
	v_mul_f32_e32 v116, 0xbfb8aa3b, v114
	v_mul_f32_e32 v117, 0xbfb8aa3b, v115
	v_exp_f32_e32 v116, v116
	v_exp_f32_e32 v117, v117
	v_add_f32_e32 v116, 1.0, v116
	v_add_f32_e32 v117, 1.0, v117
	v_rcp_f32_e32 v116, v116
	v_rcp_f32_e32 v117, v117
	s_nop 0
	v_pk_mul_f32 v[114:115], v[114:115], v[116:117]
	v_pk_mul_f32 v[116:117], v[124:125], v[134:135] op_sel_hi:[1,0]
	s_nop 0
	v_pk_mul_f32 v[124:125], v[116:117], v[114:115]
	v_cvt_pk_bf16_f32 v114, v118, v119
	v_cvt_pk_bf16_f32 v115, v120, v121
	v_cvt_pk_bf16_f32 v116, v122, v123
	v_cvt_pk_bf16_f32 v117, v124, v125
	global_store_dwordx4 v[126:127], v[114:117], off
	s_nop 1
	v_or_b32_e32 v116, 32, v156
	v_ashrrev_i32_e32 v117, 31, v116
	v_mad_i64_i32 v[114:115], s[16:17], v116, s50, v[158:159]
	v_lshl_add_u64 v[116:117], v[116:117], 2, s[2:3]
	v_mov_b32_e32 v116, v197
; DI u32x4 pack8f(const float (&f)[8]) { u32x4 w; w.x = pk2(f[0], f[1]); w.y = pk2(f[2], f[3]); w.z = pk2(f[4], f[5]); w.w = pk2(f[6], f[7]); return w; }
; DI float siluf_(float x) { return x * sigmoidf_(x); }
;     DI void operator()(AccRef acc, const Unit& u, int wr, int wc, int fr, int fq) const {
;     ...
;             for (int m = 0; m < 4; ++m) { const int row = row0 + ai * 128 + m * 16; bf16_t* rowp = O + (size_t)row * ldc + col0; const float rr = rs[row];
;                 float r[8];
; #pragma unroll
;                 for (int n = 0; n < 2; ++n)
; #pragma unroll
;                     for (int e = 0; e < 4; ++e) r[4 * n + e] = siluf_(acc[ai][0][m][n][e] * rr) * (acc[ai][1][m][n][e] * rr);
;                 *(u32x4*)rowp = pack8f(r); }
	v_pk_mul_f32 v[102:103], v[102:103], v[116:117] op_sel_hi:[1,0]
	s_nop 0
	v_mul_f32_e32 v117, 0xbfb8aa3b, v102
	v_exp_f32_e32 v117, v117
	s_nop 0
	v_add_f32_e32 v117, 1.0, v117
	v_rcp_f32_e32 v118, v117
	v_mul_f32_e32 v117, 0xbfb8aa3b, v103
	v_exp_f32_e32 v117, v117
	s_nop 0
	v_add_f32_e32 v117, 1.0, v117
	v_rcp_f32_e32 v119, v117
	v_pk_mul_f32 v[110:111], v[110:111], v[116:117] op_sel_hi:[1,0]
	v_pk_mul_f32 v[104:105], v[104:105], v[116:117] op_sel_hi:[1,0]
	v_pk_mul_f32 v[98:99], v[98:99], v[116:117] op_sel_hi:[1,0]
	v_pk_mul_f32 v[102:103], v[102:103], v[118:119]
	v_pk_mul_f32 v[106:107], v[106:107], v[116:117] op_sel_hi:[1,0]
	v_pk_mul_f32 v[102:103], v[110:111], v[102:103]
	v_mul_f32_e32 v110, 0xbfb8aa3b, v104
	v_mul_f32_e32 v111, 0xbfb8aa3b, v105
	v_exp_f32_e32 v110, v110
	v_exp_f32_e32 v111, v111
	v_add_f32_e32 v110, 1.0, v110
	v_add_f32_e32 v111, 1.0, v111
	v_rcp_f32_e32 v110, v110
	v_rcp_f32_e32 v111, v111
	s_nop 0
	v_pk_mul_f32 v[104:105], v[104:105], v[110:111]
	v_pk_mul_f32 v[110:111], v[112:113], v[116:117] op_sel_hi:[1,0]
	s_nop 0
	v_pk_mul_f32 v[104:105], v[110:111], v[104:105]
	v_mul_f32_e32 v110, 0xbfb8aa3b, v98
	v_mul_f32_e32 v111, 0xbfb8aa3b, v99
	v_exp_f32_e32 v110, v110
	v_exp_f32_e32 v111, v111
	v_add_f32_e32 v110, 1.0, v110
	v_add_f32_e32 v111, 1.0, v111
	v_rcp_f32_e32 v110, v110
	v_rcp_f32_e32 v111, v111
	s_nop 0
	v_pk_mul_f32 v[98:99], v[98:99], v[110:111]
	s_nop 0
	v_pk_mul_f32 v[106:107], v[106:107], v[98:99]
	v_pk_mul_f32 v[98:99], v[100:101], v[116:117] op_sel_hi:[1,0]
	v_lshl_add_u64 v[110:111], v[114:115], 0, v[130:131]
	v_mul_f32_e32 v100, 0xbfb8aa3b, v98
	v_mul_f32_e32 v101, 0xbfb8aa3b, v99
	v_exp_f32_e32 v100, v100
	v_exp_f32_e32 v101, v101
	v_add_f32_e32 v100, 1.0, v100
	v_add_f32_e32 v101, 1.0, v101
	v_rcp_f32_e32 v100, v100
	v_rcp_f32_e32 v101, v101
	s_nop 0
	v_pk_mul_f32 v[98:99], v[98:99], v[100:101]
	v_pk_mul_f32 v[100:101], v[108:109], v[116:117] op_sel_hi:[1,0]
	s_nop 0
	v_pk_mul_f32 v[108:109], v[100:101], v[98:99]
	v_cvt_pk_bf16_f32 v98, v102, v103
	v_cvt_pk_bf16_f32 v99, v104, v105
	v_cvt_pk_bf16_f32 v100, v106, v107
	v_cvt_pk_bf16_f32 v101, v108, v109
	global_store_dwordx4 v[110:111], v[98:101], off
	s_nop 1
	v_or_b32_e32 v100, 48, v156
	v_ashrrev_i32_e32 v101, 31, v100
	v_mad_i64_i32 v[98:99], s[16:17], v100, s50, v[158:159]
	v_lshl_add_u64 v[100:101], v[100:101], 2, s[2:3]
	v_mov_b32_e32 v100, v198
	v_pk_mul_f32 v[68:69], v[68:69], v[100:101] op_sel_hi:[1,0]
	s_nop 0
	v_mul_f32_e32 v101, 0xbfb8aa3b, v68
	v_exp_f32_e32 v101, v101
	s_nop 0
	v_add_f32_e32 v101, 1.0, v101
	v_rcp_f32_e32 v102, v101
	v_mul_f32_e32 v101, 0xbfb8aa3b, v69
	v_exp_f32_e32 v101, v101
	s_nop 0
	v_add_f32_e32 v101, 1.0, v101
	v_rcp_f32_e32 v103, v101
	v_pk_mul_f32 v[76:77], v[76:77], v[100:101] op_sel_hi:[1,0]
	v_pk_mul_f32 v[70:71], v[70:71], v[100:101] op_sel_hi:[1,0]
	v_pk_mul_f32 v[64:65], v[64:65], v[100:101] op_sel_hi:[1,0]
	v_pk_mul_f32 v[68:69], v[68:69], v[102:103]
	v_pk_mul_f32 v[72:73], v[72:73], v[100:101] op_sel_hi:[1,0]
	v_pk_mul_f32 v[68:69], v[76:77], v[68:69]
	v_mul_f32_e32 v76, 0xbfb8aa3b, v70
	v_mul_f32_e32 v77, 0xbfb8aa3b, v71
	v_exp_f32_e32 v76, v76
	v_exp_f32_e32 v77, v77
	v_pk_mul_f32 v[66:67], v[66:67], v[100:101] op_sel_hi:[1,0]
	v_cvt_pk_bf16_f32 v68, v68, v69
	v_add_f32_e32 v76, 1.0, v76
	v_add_f32_e32 v77, 1.0, v77
	v_rcp_f32_e32 v76, v76
	v_rcp_f32_e32 v77, v77
	s_nop 0
	v_pk_mul_f32 v[70:71], v[70:71], v[76:77]
	v_pk_mul_f32 v[76:77], v[78:79], v[100:101] op_sel_hi:[1,0]
	s_nop 0
	v_pk_mul_f32 v[70:71], v[76:77], v[70:71]
	v_mul_f32_e32 v76, 0xbfb8aa3b, v64
	v_mul_f32_e32 v77, 0xbfb8aa3b, v65
	v_exp_f32_e32 v76, v76
	v_exp_f32_e32 v77, v77
	v_cvt_pk_bf16_f32 v69, v70, v71
	v_add_f32_e32 v76, 1.0, v76
	v_add_f32_e32 v77, 1.0, v77
	v_rcp_f32_e32 v76, v76
	v_rcp_f32_e32 v77, v77
	s_nop 0
	v_pk_mul_f32 v[64:65], v[64:65], v[76:77]
	s_nop 0
	v_pk_mul_f32 v[64:65], v[72:73], v[64:65]
	v_mul_f32_e32 v72, 0xbfb8aa3b, v66
	v_mul_f32_e32 v73, 0xbfb8aa3b, v67
	v_exp_f32_e32 v72, v72
	v_exp_f32_e32 v73, v73
	v_cvt_pk_bf16_f32 v70, v64, v65
	v_add_u32_e32 v64, 0x80, v156
	v_add_f32_e32 v72, 1.0, v72
	v_add_f32_e32 v73, 1.0, v73
	v_rcp_f32_e32 v72, v72
	v_rcp_f32_e32 v73, v73
	v_mad_i64_i32 v[64:65], s[16:17], v64, s50, v[158:159]
	v_pk_mul_f32 v[66:67], v[66:67], v[72:73]
	v_pk_mul_f32 v[72:73], v[74:75], v[100:101] op_sel_hi:[1,0]
	s_nop 0
	v_pk_mul_f32 v[66:67], v[72:73], v[66:67]
	v_lshl_add_u64 v[72:73], v[98:99], 0, v[130:131]
	v_cvt_pk_bf16_f32 v71, v66, v67
	global_store_dwordx4 v[72:73], v[68:71], off
	v_mov_b32_e32 v66, v199
	v_pk_mul_f32 v[52:53], v[52:53], v[66:67] op_sel_hi:[1,0]
	s_nop 0
	v_mul_f32_e32 v67, 0xbfb8aa3b, v52
	v_exp_f32_e32 v67, v67
	s_nop 0
	v_add_f32_e32 v67, 1.0, v67
	v_rcp_f32_e32 v68, v67
	v_mul_f32_e32 v67, 0xbfb8aa3b, v53
	v_exp_f32_e32 v67, v67
	s_nop 0
	v_add_f32_e32 v67, 1.0, v67
	v_rcp_f32_e32 v69, v67
	v_pk_mul_f32 v[60:61], v[60:61], v[66:67] op_sel_hi:[1,0]
	v_pk_mul_f32 v[54:55], v[54:55], v[66:67] op_sel_hi:[1,0]
	v_pk_mul_f32 v[48:49], v[48:49], v[66:67] op_sel_hi:[1,0]
	v_pk_mul_f32 v[52:53], v[52:53], v[68:69]
	v_pk_mul_f32 v[56:57], v[56:57], v[66:67] op_sel_hi:[1,0]
	v_pk_mul_f32 v[52:53], v[60:61], v[52:53]
	v_mul_f32_e32 v60, 0xbfb8aa3b, v54
	v_mul_f32_e32 v61, 0xbfb8aa3b, v55
	v_exp_f32_e32 v60, v60
	v_exp_f32_e32 v61, v61
	v_pk_mul_f32 v[50:51], v[50:51], v[66:67] op_sel_hi:[1,0]
	v_cvt_pk_bf16_f32 v52, v52, v53
	v_add_f32_e32 v60, 1.0, v60
	v_add_f32_e32 v61, 1.0, v61
	v_rcp_f32_e32 v60, v60
	v_rcp_f32_e32 v61, v61
	s_nop 0
	v_pk_mul_f32 v[54:55], v[54:55], v[60:61]
	v_pk_mul_f32 v[60:61], v[62:63], v[66:67] op_sel_hi:[1,0]
	s_nop 0
; DI u32x4 pack8f(const float (&f)[8]) { u32x4 w; w.x = pk2(f[0], f[1]); w.y = pk2(f[2], f[3]); w.z = pk2(f[4], f[5]); w.w = pk2(f[6], f[7]); return w; }
; DI float siluf_(float x) { return x * sigmoidf_(x); }
;     DI void operator()(AccRef acc, const Unit& u, int wr, int wc, int fr, int fq) const {
;     ...
;             for (int m = 0; m < 4; ++m) { const int row = row0 + ai * 128 + m * 16; bf16_t* rowp = O + (size_t)row * ldc + col0; const float rr = rs[row];
;                 float r[8];
; #pragma unroll
;                 for (int n = 0; n < 2; ++n)
; #pragma unroll
;                     for (int e = 0; e < 4; ++e) r[4 * n + e] = siluf_(acc[ai][0][m][n][e] * rr) * (acc[ai][1][m][n][e] * rr);
;                 *(u32x4*)rowp = pack8f(r); }
	v_pk_mul_f32 v[54:55], v[60:61], v[54:55]
	v_mul_f32_e32 v60, 0xbfb8aa3b, v48
	v_mul_f32_e32 v61, 0xbfb8aa3b, v49
	v_exp_f32_e32 v60, v60
	v_exp_f32_e32 v61, v61
	v_cvt_pk_bf16_f32 v53, v54, v55
	v_add_f32_e32 v60, 1.0, v60
	v_add_f32_e32 v61, 1.0, v61
	v_rcp_f32_e32 v60, v60
	v_rcp_f32_e32 v61, v61
	s_nop 0
	v_pk_mul_f32 v[48:49], v[48:49], v[60:61]
	s_nop 0
	v_pk_mul_f32 v[48:49], v[56:57], v[48:49]
	v_mul_f32_e32 v56, 0xbfb8aa3b, v50
	v_mul_f32_e32 v57, 0xbfb8aa3b, v51
	v_exp_f32_e32 v56, v56
	v_exp_f32_e32 v57, v57
	v_cvt_pk_bf16_f32 v54, v48, v49
	v_add_u32_e32 v48, 0x90, v156
	v_add_f32_e32 v56, 1.0, v56
	v_add_f32_e32 v57, 1.0, v57
	v_rcp_f32_e32 v56, v56
	v_rcp_f32_e32 v57, v57
	v_mad_i64_i32 v[48:49], s[16:17], v48, s50, v[158:159]
	v_pk_mul_f32 v[50:51], v[50:51], v[56:57]
	v_pk_mul_f32 v[56:57], v[58:59], v[66:67] op_sel_hi:[1,0]
	s_nop 0
	v_pk_mul_f32 v[50:51], v[56:57], v[50:51]
	v_lshl_add_u64 v[56:57], v[64:65], 0, v[130:131]
	v_cvt_pk_bf16_f32 v55, v50, v51
	global_store_dwordx4 v[56:57], v[52:55], off
	v_mov_b32_e32 v50, v200
	v_pk_mul_f32 v[36:37], v[36:37], v[50:51] op_sel_hi:[1,0]
	s_nop 0
	v_mul_f32_e32 v51, 0xbfb8aa3b, v36
	v_exp_f32_e32 v51, v51
	s_nop 0
	v_add_f32_e32 v51, 1.0, v51
	v_rcp_f32_e32 v52, v51
	v_mul_f32_e32 v51, 0xbfb8aa3b, v37
	v_exp_f32_e32 v51, v51
	s_nop 0
	v_add_f32_e32 v51, 1.0, v51
	v_rcp_f32_e32 v53, v51
	v_pk_mul_f32 v[44:45], v[44:45], v[50:51] op_sel_hi:[1,0]
	v_pk_mul_f32 v[38:39], v[38:39], v[50:51] op_sel_hi:[1,0]
	v_pk_mul_f32 v[32:33], v[32:33], v[50:51] op_sel_hi:[1,0]
	v_pk_mul_f32 v[36:37], v[36:37], v[52:53]
	v_pk_mul_f32 v[40:41], v[40:41], v[50:51] op_sel_hi:[1,0]
	v_pk_mul_f32 v[36:37], v[44:45], v[36:37]
	v_mul_f32_e32 v44, 0xbfb8aa3b, v38
	v_mul_f32_e32 v45, 0xbfb8aa3b, v39
	v_exp_f32_e32 v44, v44
	v_exp_f32_e32 v45, v45
	v_pk_mul_f32 v[34:35], v[34:35], v[50:51] op_sel_hi:[1,0]
	v_cvt_pk_bf16_f32 v36, v36, v37
	v_add_f32_e32 v44, 1.0, v44
	v_add_f32_e32 v45, 1.0, v45
	v_rcp_f32_e32 v44, v44
	v_rcp_f32_e32 v45, v45
	s_nop 0
	v_pk_mul_f32 v[38:39], v[38:39], v[44:45]
	v_pk_mul_f32 v[44:45], v[46:47], v[50:51] op_sel_hi:[1,0]
	s_nop 0
	v_pk_mul_f32 v[38:39], v[44:45], v[38:39]
	v_mul_f32_e32 v44, 0xbfb8aa3b, v32
	v_mul_f32_e32 v45, 0xbfb8aa3b, v33
	v_exp_f32_e32 v44, v44
	v_exp_f32_e32 v45, v45
	v_cvt_pk_bf16_f32 v37, v38, v39
	v_add_f32_e32 v44, 1.0, v44
	v_add_f32_e32 v45, 1.0, v45
	v_rcp_f32_e32 v44, v44
	v_rcp_f32_e32 v45, v45
	s_nop 0
	v_pk_mul_f32 v[32:33], v[32:33], v[44:45]
	s_nop 0
	v_pk_mul_f32 v[32:33], v[40:41], v[32:33]
	v_mul_f32_e32 v40, 0xbfb8aa3b, v34
	v_mul_f32_e32 v41, 0xbfb8aa3b, v35
	v_exp_f32_e32 v40, v40
	v_exp_f32_e32 v41, v41
	v_cvt_pk_bf16_f32 v38, v32, v33
	v_add_u32_e32 v32, 0xa0, v156
	v_add_f32_e32 v40, 1.0, v40
	v_add_f32_e32 v41, 1.0, v41
	v_rcp_f32_e32 v40, v40
	v_rcp_f32_e32 v41, v41
	v_mad_i64_i32 v[32:33], s[16:17], v32, s50, v[158:159]
	v_pk_mul_f32 v[34:35], v[34:35], v[40:41]
	v_pk_mul_f32 v[40:41], v[42:43], v[50:51] op_sel_hi:[1,0]
	s_nop 0
	v_pk_mul_f32 v[34:35], v[40:41], v[34:35]
	v_lshl_add_u64 v[40:41], v[48:49], 0, v[130:131]
	v_cvt_pk_bf16_f32 v39, v34, v35
	global_store_dwordx4 v[40:41], v[36:39], off
	v_mov_b32_e32 v34, v201
	v_pk_mul_f32 v[20:21], v[20:21], v[34:35] op_sel_hi:[1,0]
	s_nop 0
	v_mul_f32_e32 v35, 0xbfb8aa3b, v20
	v_exp_f32_e32 v35, v35
	s_nop 0
	v_add_f32_e32 v35, 1.0, v35
	v_rcp_f32_e32 v36, v35
	v_mul_f32_e32 v35, 0xbfb8aa3b, v21
	v_exp_f32_e32 v35, v35
	s_nop 0
	v_add_f32_e32 v35, 1.0, v35
	v_rcp_f32_e32 v37, v35
	v_pk_mul_f32 v[28:29], v[28:29], v[34:35] op_sel_hi:[1,0]
	v_pk_mul_f32 v[22:23], v[22:23], v[34:35] op_sel_hi:[1,0]
	v_pk_mul_f32 v[16:17], v[16:17], v[34:35] op_sel_hi:[1,0]
	v_pk_mul_f32 v[20:21], v[20:21], v[36:37]
	v_pk_mul_f32 v[24:25], v[24:25], v[34:35] op_sel_hi:[1,0]
	v_pk_mul_f32 v[20:21], v[28:29], v[20:21]
	v_mul_f32_e32 v28, 0xbfb8aa3b, v22
	v_mul_f32_e32 v29, 0xbfb8aa3b, v23
	v_exp_f32_e32 v28, v28
	v_exp_f32_e32 v29, v29
	v_pk_mul_f32 v[18:19], v[18:19], v[34:35] op_sel_hi:[1,0]
	v_cvt_pk_bf16_f32 v20, v20, v21
	v_add_f32_e32 v28, 1.0, v28
; DI u32x4 pack8f(const float (&f)[8]) { u32x4 w; w.x = pk2(f[0], f[1]); w.y = pk2(f[2], f[3]); w.z = pk2(f[4], f[5]); w.w = pk2(f[6], f[7]); return w; }
; DI float siluf_(float x) { return x * sigmoidf_(x); }
; #define PG8_BAR __builtin_amdgcn_s_barrier()
; template <class Epi>
; DI void gemm_phase(LAS unsigned char* lds, const Gemm g, const StaticOrder& S, const Epi& E) {
;     ...
;         if (!has_next) break;
; #pragma unroll
;         for (int a = 0; a < 2; ++a)
; #pragma unroll
;             for (int b = 0; b < 2; ++b)
; #pragma unroll
;                 for (int m = 0; m < 4; ++m)
; #pragma unroll
;                     for (int n = 0; n < 2; ++n) { float zz = 0.f; asm volatile("" : "+v"(zz)); acc[a][b][m][n] = (f32x4){zz, zz, zz, zz}; }
;         cur = nxt; cA = nA; cB = nB; ++ui;
;         if (wr == 1) PG8_BAR;
;     DI void operator()(AccRef acc, const Unit& u, int wr, int wc, int fr, int fq) const {
;     ...
;             for (int m = 0; m < 4; ++m) { const int row = row0 + ai * 128 + m * 16; bf16_t* rowp = O + (size_t)row * ldc + col0; const float rr = rs[row];
;                 float r[8];
; #pragma unroll
;                 for (int n = 0; n < 2; ++n)
; #pragma unroll
;                     for (int e = 0; e < 4; ++e) r[4 * n + e] = siluf_(acc[ai][0][m][n][e] * rr) * (acc[ai][1][m][n][e] * rr);
;                 *(u32x4*)rowp = pack8f(r); }
	v_add_f32_e32 v29, 1.0, v29
	v_rcp_f32_e32 v28, v28
	v_rcp_f32_e32 v29, v29
	s_nop 0
	v_pk_mul_f32 v[22:23], v[22:23], v[28:29]
	v_pk_mul_f32 v[28:29], v[30:31], v[34:35] op_sel_hi:[1,0]
	s_nop 0
	v_pk_mul_f32 v[22:23], v[28:29], v[22:23]
	v_mul_f32_e32 v28, 0xbfb8aa3b, v16
	v_mul_f32_e32 v29, 0xbfb8aa3b, v17
	v_exp_f32_e32 v28, v28
	v_exp_f32_e32 v29, v29
	v_cvt_pk_bf16_f32 v21, v22, v23
	v_add_f32_e32 v28, 1.0, v28
	v_add_f32_e32 v29, 1.0, v29
	v_rcp_f32_e32 v28, v28
	v_rcp_f32_e32 v29, v29
	s_nop 0
	v_pk_mul_f32 v[16:17], v[16:17], v[28:29]
	s_nop 0
	v_pk_mul_f32 v[16:17], v[24:25], v[16:17]
	v_mul_f32_e32 v24, 0xbfb8aa3b, v18
	v_mul_f32_e32 v25, 0xbfb8aa3b, v19
	v_exp_f32_e32 v24, v24
	v_exp_f32_e32 v25, v25
	v_cvt_pk_bf16_f32 v22, v16, v17
	v_add_u32_e32 v16, 0xb0, v156
	v_add_f32_e32 v24, 1.0, v24
	v_add_f32_e32 v25, 1.0, v25
	v_rcp_f32_e32 v24, v24
	v_rcp_f32_e32 v25, v25
	v_mad_i64_i32 v[16:17], s[16:17], v16, s50, v[158:159]
	s_mov_b64 s[16:17], -1
	v_pk_mul_f32 v[18:19], v[18:19], v[24:25]
	v_pk_mul_f32 v[24:25], v[26:27], v[34:35] op_sel_hi:[1,0]
	s_nop 0
	v_pk_mul_f32 v[18:19], v[24:25], v[18:19]
	v_lshl_add_u64 v[24:25], v[32:33], 0, v[130:131]
	v_cvt_pk_bf16_f32 v23, v18, v19
	global_store_dwordx4 v[24:25], v[20:23], off
	v_mov_b32_e32 v18, v202
	v_pk_mul_f32 v[4:5], v[4:5], v[18:19] op_sel_hi:[1,0]
	s_nop 0
	v_mul_f32_e32 v19, 0xbfb8aa3b, v4
	v_exp_f32_e32 v19, v19
	s_nop 0
	v_add_f32_e32 v19, 1.0, v19
	v_rcp_f32_e32 v20, v19
	v_mul_f32_e32 v19, 0xbfb8aa3b, v5
	v_exp_f32_e32 v19, v19
	s_nop 0
	v_add_f32_e32 v19, 1.0, v19
	v_rcp_f32_e32 v21, v19
	v_pk_mul_f32 v[12:13], v[12:13], v[18:19] op_sel_hi:[1,0]
	v_pk_mul_f32 v[6:7], v[6:7], v[18:19] op_sel_hi:[1,0]
	v_pk_mul_f32 v[0:1], v[0:1], v[18:19] op_sel_hi:[1,0]
	v_pk_mul_f32 v[4:5], v[4:5], v[20:21]
	v_pk_mul_f32 v[8:9], v[8:9], v[18:19] op_sel_hi:[1,0]
	v_pk_mul_f32 v[4:5], v[12:13], v[4:5]
	v_mul_f32_e32 v12, 0xbfb8aa3b, v6
	v_mul_f32_e32 v13, 0xbfb8aa3b, v7
	v_exp_f32_e32 v12, v12
	v_exp_f32_e32 v13, v13
	v_add_f32_e32 v12, 1.0, v12
	v_add_f32_e32 v13, 1.0, v13
	v_rcp_f32_e32 v12, v12
	v_rcp_f32_e32 v13, v13
	s_nop 0
	v_pk_mul_f32 v[6:7], v[6:7], v[12:13]
	v_pk_mul_f32 v[12:13], v[14:15], v[18:19] op_sel_hi:[1,0]
	s_nop 0
	v_pk_mul_f32 v[6:7], v[12:13], v[6:7]
	v_mul_f32_e32 v12, 0xbfb8aa3b, v0
	v_mul_f32_e32 v13, 0xbfb8aa3b, v1
	v_exp_f32_e32 v12, v12
	v_exp_f32_e32 v13, v13
	v_add_f32_e32 v12, 1.0, v12
	v_add_f32_e32 v13, 1.0, v13
	v_rcp_f32_e32 v12, v12
	v_rcp_f32_e32 v13, v13
	s_nop 0
	v_pk_mul_f32 v[0:1], v[0:1], v[12:13]
	s_nop 0
	v_pk_mul_f32 v[8:9], v[8:9], v[0:1]
	v_pk_mul_f32 v[0:1], v[2:3], v[18:19] op_sel_hi:[1,0]
	v_lshl_add_u64 v[12:13], v[16:17], 0, v[130:131]
	v_mul_f32_e32 v2, 0xbfb8aa3b, v0
	v_mul_f32_e32 v3, 0xbfb8aa3b, v1
	v_exp_f32_e32 v2, v2
	v_exp_f32_e32 v3, v3
	v_add_f32_e32 v2, 1.0, v2
	v_add_f32_e32 v3, 1.0, v3
	v_rcp_f32_e32 v2, v2
	v_rcp_f32_e32 v3, v3
	s_nop 0
	v_pk_mul_f32 v[0:1], v[0:1], v[2:3]
	v_pk_mul_f32 v[2:3], v[10:11], v[18:19] op_sel_hi:[1,0]
	s_nop 0
	v_pk_mul_f32 v[10:11], v[2:3], v[0:1]
	v_cvt_pk_bf16_f32 v0, v4, v5
	v_cvt_pk_bf16_f32 v1, v6, v7
	v_cvt_pk_bf16_f32 v2, v8, v9
	v_cvt_pk_bf16_f32 v3, v10, v11
	global_store_dwordx4 v[12:13], v[0:3], off
	s_cbranch_vccnz .LBB0_697
	v_mov_b32_e32 v134, 0
	v_mov_b32_e32 v130, 0
	v_mov_b32_e32 v118, 0
	v_mov_b32_e32 v114, 0
	v_mov_b32_e32 v102, 0
	v_mov_b32_e32 v98, 0
	v_mov_b32_e32 v68, 0
	v_mov_b32_e32 v64, 0
	v_mov_b32_e32 v142, 0
	v_mov_b32_e32 v138, 0
	v_mov_b32_e32 v126, 0
	v_mov_b32_e32 v122, 0
	v_mov_b32_e32 v110, 0
	v_mov_b32_e32 v106, 0
	v_mov_b32_e32 v76, 0
	v_mov_b32_e32 v72, 0
	v_mov_b32_e32 v52, 0
	v_mov_b32_e32 v48, 0
	v_mov_b32_e32 v36, 0
	v_mov_b32_e32 v32, 0
	v_mov_b32_e32 v20, 0
	v_mov_b32_e32 v16, 0
	v_mov_b32_e32 v4, 0
	v_mov_b32_e32 v0, 0
	v_mov_b32_e32 v60, 0
	v_mov_b32_e32 v56, 0
	v_mov_b32_e32 v44, 0
	v_mov_b32_e32 v40, 0
	v_mov_b32_e32 v28, 0
	v_mov_b32_e32 v24, 0
	v_mov_b32_e32 v12, 0
	v_mov_b32_e32 v8, 0
	s_andn2_b64 vcc, exec, s[0:1]
	s_cbranch_vccnz .LBB0_696
	s_barrier
	s_branch .LBB0_696
